# rwkv in-proj k-loop: A/B fragment ds_reads double-buffered one k-step ahead and hoisted above the prefetch issue
# speedup vs baseline: 1.1357x; 1.0014x over previous
.LBB0_760:
	s_add_u32 s58, s58, 0x100
	s_addc_u32 s59, s59, 0
	s_waitcnt lgkmcnt(4)
	v_mfma_f32_32x32x16_bf16 v[0:15], v[116:119], v[120:123], v[0:15]
	v_lshl_add_u64 v[134:135], v[134:135], 0, s[54:55]
	v_lshl_add_u64 v[136:137], v[136:137], 0, s[54:55]
	v_lshl_add_u64 v[138:139], v[138:139], 0, s[54:55]
	v_mfma_f32_32x32x16_bf16 v[48:63], v[222:225], v[120:123], v[48:63]
	v_lshl_add_u64 v[140:141], v[140:141], 0, s[54:55]
	v_lshl_add_u64 v[142:143], v[142:143], 0, s[54:55]
	v_lshl_add_u64 v[144:145], v[144:145], 0, s[54:55]
	v_mfma_f32_32x32x16_bf16 v[32:47], v[116:119], v[226:229], v[32:47]
	v_lshl_add_u64 v[146:147], v[146:147], 0, s[54:55]
	v_lshl_add_u64 v[148:149], v[148:149], 0, s[54:55]
	v_lshl_add_u64 v[150:151], v[150:151], 0, s[54:55]
	v_mfma_f32_32x32x16_bf16 v[16:31], v[222:225], v[226:229], v[16:31]
	v_lshl_add_u64 v[188:189], v[188:189], 0, s[54:55]
	v_lshl_add_u64 v[190:191], v[190:191], 0, s[54:55]
	v_lshl_add_u64 v[192:193], v[192:193], 0, s[54:55]
	s_cmpk_lg_i32 s58, 0x1000
	ds_read_b128 v[116:119], v173 offset:18496
	ds_read_b128 v[120:123], v163 offset:64
	ds_read_b128 v[222:225], v173 offset:23104
	ds_read_b128 v[226:229], v163 offset:4672
	s_waitcnt lgkmcnt(4)
	v_mfma_f32_32x32x16_bf16 v[0:15], v[230:233], v[238:241], v[0:15]
	v_mfma_f32_32x32x16_bf16 v[48:63], v[234:237], v[238:241], v[48:63]
	v_mfma_f32_32x32x16_bf16 v[32:47], v[230:233], v[242:245], v[32:47]
	v_mfma_f32_32x32x16_bf16 v[16:31], v[234:237], v[242:245], v[16:31]
	ds_read_b128 v[230:233], v173 offset:18528
	ds_read_b128 v[238:241], v163 offset:96
	ds_read_b128 v[234:237], v173 offset:23136
	ds_read_b128 v[242:245], v163 offset:4704
	s_waitcnt lgkmcnt(4)
	v_mfma_f32_32x32x16_bf16 v[0:15], v[116:119], v[120:123], v[0:15]
	v_mfma_f32_32x32x16_bf16 v[48:63], v[222:225], v[120:123], v[48:63]
	v_mfma_f32_32x32x16_bf16 v[32:47], v[116:119], v[226:229], v[32:47]
	v_mfma_f32_32x32x16_bf16 v[16:31], v[222:225], v[226:229], v[16:31]
	s_waitcnt lgkmcnt(0)
	v_mfma_f32_32x32x16_bf16 v[0:15], v[230:233], v[238:241], v[0:15]
	v_mfma_f32_32x32x16_bf16 v[48:63], v[234:237], v[238:241], v[48:63]
	v_mfma_f32_32x32x16_bf16 v[32:47], v[230:233], v[242:245], v[32:47]
	v_mfma_f32_32x32x16_bf16 v[16:31], v[234:237], v[242:245], v[16:31]
	s_cbranch_scc0 .LBB0_785
.LBB0_761:
	v_lshl_add_u64 v[66:67], v[202:203], 0, s[58:59]
	s_barrier
	ds_read_b128 v[116:119], v255 offset:16
	ds_read_b128 v[120:123], v255
	v_add_u32_e32 v255, 0x100, v255
	s_waitcnt vmcnt(7)
	v_lshlrev_b32_e32 v65, 16, v68
	v_lshlrev_b32_e32 v66, 16, v72
	v_sub_f32_e32 v66, v66, v65
	v_and_b32_e32 v67, 0xffff0000, v72
	v_lshlrev_b32_e32 v221, 16, v73
	v_and_b32_e32 v222, 0xffff0000, v73
	v_lshlrev_b32_e32 v224, 16, v70
	v_and_b32_e32 v225, 0xffff0000, v70
	v_lshlrev_b32_e32 v226, 16, v71
	v_and_b32_e32 v227, 0xffff0000, v71
	s_cmpk_eq_i32 s58, 0xf00
	s_waitcnt vmcnt(0) lgkmcnt(0)
	v_fmac_f32_e32 v65, v120, v66
	v_and_b32_e32 v66, 0xffff0000, v68
	v_sub_f32_e32 v67, v67, v66
	v_fmac_f32_e32 v66, v67, v121
	v_lshlrev_b32_e32 v67, 16, v69
	v_sub_f32_e32 v221, v221, v67
	v_fmac_f32_e32 v67, v221, v122
	v_and_b32_e32 v221, 0xffff0000, v69
	v_sub_f32_e32 v222, v222, v221
	v_fmac_f32_e32 v221, v222, v123
	v_lshlrev_b32_e32 v222, 16, v74
	v_sub_f32_e32 v222, v222, v224
	v_fmac_f32_e32 v224, v222, v116
	v_and_b32_e32 v222, 0xffff0000, v74
	v_sub_f32_e32 v222, v222, v225
	v_fmac_f32_e32 v225, v222, v117
	v_lshlrev_b32_e32 v222, 16, v75
	v_sub_f32_e32 v222, v222, v226
	v_fmac_f32_e32 v226, v222, v118
	v_and_b32_e32 v222, 0xffff0000, v75
	v_sub_f32_e32 v222, v222, v227
	v_fmac_f32_e32 v227, v222, v119
	v_cvt_pk_bf16_f32 v222, v65, v66
	v_lshlrev_b32_e32 v65, 16, v80
	v_lshlrev_b32_e32 v66, 16, v84
	v_sub_f32_e32 v66, v66, v65
	v_cvt_pk_bf16_f32 v223, v67, v221
	v_fmac_f32_e32 v65, v66, v120
	v_and_b32_e32 v66, 0xffff0000, v80
	v_and_b32_e32 v67, 0xffff0000, v84
	v_sub_f32_e32 v67, v67, v66
	v_fmac_f32_e32 v66, v67, v121
	v_lshlrev_b32_e32 v67, 16, v81
	v_lshlrev_b32_e32 v221, 16, v85
	v_cvt_pk_bf16_f32 v224, v224, v225
	v_cvt_pk_bf16_f32 v225, v226, v227
	v_sub_f32_e32 v221, v221, v67
	ds_write_b128 v161, v[222:225]
	ds_write_b128 v161, v[76:79] offset:18432
	v_fmac_f32_e32 v67, v221, v122
	v_and_b32_e32 v221, 0xffff0000, v81
	v_and_b32_e32 v222, 0xffff0000, v85
	v_sub_f32_e32 v222, v222, v221
	v_fmac_f32_e32 v221, v222, v123
	v_lshlrev_b32_e32 v224, 16, v82
	v_lshlrev_b32_e32 v222, 16, v86
	v_sub_f32_e32 v222, v222, v224
	v_fmac_f32_e32 v224, v222, v116
	v_and_b32_e32 v225, 0xffff0000, v82
	v_and_b32_e32 v222, 0xffff0000, v86
	v_sub_f32_e32 v222, v222, v225
	v_fmac_f32_e32 v225, v222, v117
	v_lshlrev_b32_e32 v226, 16, v83
	v_lshlrev_b32_e32 v222, 16, v87
	v_sub_f32_e32 v222, v222, v226
	v_fmac_f32_e32 v226, v222, v118
	v_and_b32_e32 v227, 0xffff0000, v83
	v_and_b32_e32 v222, 0xffff0000, v87
	v_sub_f32_e32 v222, v222, v227
	v_fmac_f32_e32 v227, v222, v119
	v_cvt_pk_bf16_f32 v222, v65, v66
	v_lshlrev_b32_e32 v65, 16, v92
	v_lshlrev_b32_e32 v66, 16, v96
	v_sub_f32_e32 v66, v66, v65
	v_cvt_pk_bf16_f32 v223, v67, v221
	v_fmac_f32_e32 v65, v66, v120
	v_and_b32_e32 v66, 0xffff0000, v92
	v_and_b32_e32 v67, 0xffff0000, v96
	v_sub_f32_e32 v67, v67, v66
	v_fmac_f32_e32 v66, v67, v121
	v_lshlrev_b32_e32 v67, 16, v93
	v_lshlrev_b32_e32 v221, 16, v97
	v_cvt_pk_bf16_f32 v224, v224, v225
	v_cvt_pk_bf16_f32 v225, v226, v227
	v_sub_f32_e32 v221, v221, v67
	ds_write_b128 v161, v[222:225] offset:4608
	ds_write_b128 v161, v[88:91] offset:23040
	v_fmac_f32_e32 v67, v221, v122
	v_and_b32_e32 v221, 0xffff0000, v93
	v_and_b32_e32 v222, 0xffff0000, v97
	v_sub_f32_e32 v222, v222, v221
	v_fmac_f32_e32 v221, v222, v123
	v_lshlrev_b32_e32 v224, 16, v94
	v_lshlrev_b32_e32 v222, 16, v98
	v_sub_f32_e32 v222, v222, v224
	v_fmac_f32_e32 v224, v222, v116
	v_and_b32_e32 v225, 0xffff0000, v94
	v_and_b32_e32 v222, 0xffff0000, v98
	v_sub_f32_e32 v222, v222, v225
	v_fmac_f32_e32 v225, v222, v117
	v_lshlrev_b32_e32 v226, 16, v95
	v_lshlrev_b32_e32 v222, 16, v99
	v_sub_f32_e32 v222, v222, v226
	v_fmac_f32_e32 v226, v222, v118
	v_and_b32_e32 v227, 0xffff0000, v95
	v_and_b32_e32 v222, 0xffff0000, v99
	v_sub_f32_e32 v222, v222, v227
	v_fmac_f32_e32 v227, v222, v119
	v_cvt_pk_bf16_f32 v222, v65, v66
	v_lshlrev_b32_e32 v65, 16, v104
	v_lshlrev_b32_e32 v66, 16, v108
	v_sub_f32_e32 v66, v66, v65
	v_cvt_pk_bf16_f32 v223, v67, v221
	v_fmac_f32_e32 v65, v66, v120
	v_and_b32_e32 v66, 0xffff0000, v104
	v_and_b32_e32 v67, 0xffff0000, v108
	v_sub_f32_e32 v67, v67, v66
	v_fmac_f32_e32 v66, v67, v121
	v_lshlrev_b32_e32 v67, 16, v105
	v_lshlrev_b32_e32 v120, 16, v109
	v_sub_f32_e32 v120, v120, v67
	v_fmac_f32_e32 v67, v120, v122
	v_and_b32_e32 v120, 0xffff0000, v105
	v_and_b32_e32 v121, 0xffff0000, v109
	v_sub_f32_e32 v121, v121, v120
	v_fmac_f32_e32 v120, v121, v123
	v_lshlrev_b32_e32 v121, 16, v106
	v_lshlrev_b32_e32 v122, 16, v110
	v_sub_f32_e32 v122, v122, v121
	v_fmac_f32_e32 v121, v122, v116
	v_and_b32_e32 v122, 0xffff0000, v106
	v_and_b32_e32 v116, 0xffff0000, v110
	v_sub_f32_e32 v116, v116, v122
	v_fmac_f32_e32 v122, v116, v117
	v_lshlrev_b32_e32 v123, 16, v107
	v_lshlrev_b32_e32 v116, 16, v111
	v_sub_f32_e32 v116, v116, v123
	v_fmac_f32_e32 v123, v116, v118
	v_and_b32_e32 v221, 0xffff0000, v107
	v_and_b32_e32 v116, 0xffff0000, v111
	v_sub_f32_e32 v116, v116, v221
	v_cvt_pk_bf16_f32 v224, v224, v225
	v_cvt_pk_bf16_f32 v225, v226, v227
	v_fmac_f32_e32 v221, v116, v119
	v_cvt_pk_bf16_f32 v116, v65, v66
	v_cvt_pk_bf16_f32 v117, v67, v120
	v_cvt_pk_bf16_f32 v118, v121, v122
	v_cvt_pk_bf16_f32 v119, v123, v221
	ds_write_b128 v161, v[222:225] offset:9216
	ds_write_b128 v161, v[100:103] offset:27648
	ds_write_b128 v161, v[116:119] offset:13824
	ds_write_b128 v161, v[112:115] offset:32256
	s_waitcnt lgkmcnt(0)
	s_barrier
	ds_read_b128 v[116:119], v173 offset:18432
	ds_read_b128 v[120:123], v163
	ds_read_b128 v[222:225], v173 offset:23040
	ds_read_b128 v[226:229], v163 offset:4608
	ds_read_b128 v[230:233], v173 offset:18464
	ds_read_b128 v[238:241], v163 offset:32
	ds_read_b128 v[234:237], v173 offset:23072
	ds_read_b128 v[242:245], v163 offset:4640
	s_cbranch_scc1 .LBB0_760
	v_lshl_add_u64 v[66:67], v[142:143], 0, v[186:187]
	global_load_dwordx4 v[68:71], v[66:67], off
	s_and_saveexec_b64 s[60:61], s[16:17]
	s_xor_b64 s[60:61], exec, s[60:61]
	s_cbranch_execz .LBB0_764
	v_lshl_add_u64 v[66:67], v[144:145], 0, v[186:187]
	global_load_dwordx4 v[72:75], v[66:67], off
